# hand-written dot4 U pass with reduce-scatter + P0b mod-reduction prologue loads batched + P10a sub-key LDS fill loads batched
# speedup vs baseline: 1.0256x; 1.0160x over previous
; __device__ __forceinline__ void phase_norm(Frame& F, const Params& p, int which) {
;     ...
;         for (int i = F.tid; i < 3 * D; i += NTHREADS) {
;             const int r = i / D, k = i % D; float s0 = bada[k], s1 = bada[D + k];
;             for (int ks = 0; ks < KSL; ++ks) { s0 += modp[(size_t)(ks * 3 + r) * 12288 + k]; s1 += modp[(size_t)(ks * 3 + r) * 12288 + D + k]; }
;             gs[i] = p.in[6][k] * (1.f + s1); sh[i] = s0;
;         }
.LBB0_276:
	v_ashrrev_i32_e32 v0, 31, v7
	v_lshrrev_b32_e32 v0, 21, v0
	v_add_u32_e32 v0, v7, v0
	v_ashrrev_i32_e32 v12, 11, v0
	v_mul_i32_i24_e32 v0, 0x800, v12
	v_sub_u32_e32 v0, v7, v0
	v_ashrrev_i32_e32 v1, 31, v0
	v_lshlrev_b64 v[4:5], 2, v[0:1]
	v_lshl_add_u64 v[8:9], s[4:5], 0, v[4:5]
	v_add_co_u32_e32 v10, vcc, 0x2000, v8
	v_mad_i64_i32 v[4:5], s[18:19], v12, s7, v[4:5]
	s_nop 0
	v_addc_co_u32_e32 v11, vcc, 0, v9, vcc
	global_load_dword v2, v[8:9], off
	global_load_dword v3, v[10:11], off
	v_add_u32_e32 v5, 0x2000, v4
	s_add_u32 s18, s56, 0x100000
	s_addc_u32 s19, s57, 0
	global_load_dword v20, v4, s[18:19]
	global_load_dword v21, v5, s[18:19]
	s_add_u32 s18, s18, 0x24000
	s_addc_u32 s19, s19, 0
	global_load_dword v22, v4, s[18:19]
	global_load_dword v23, v5, s[18:19]
	s_add_u32 s18, s18, 0x24000
	s_addc_u32 s19, s19, 0
	global_load_dword v32, v4, s[18:19]
	global_load_dword v33, v5, s[18:19]
	s_add_u32 s18, s18, 0x24000
	s_addc_u32 s19, s19, 0
	global_load_dword v34, v4, s[18:19]
	global_load_dword v35, v5, s[18:19]
	s_add_u32 s18, s18, 0x24000
	s_addc_u32 s19, s19, 0
	global_load_dword v36, v4, s[18:19]
	global_load_dword v37, v5, s[18:19]
	s_add_u32 s18, s18, 0x24000
	s_addc_u32 s19, s19, 0
	global_load_dword v38, v4, s[18:19]
	global_load_dword v39, v5, s[18:19]
	s_add_u32 s18, s18, 0x24000
	s_addc_u32 s19, s19, 0
	global_load_dword v40, v4, s[18:19]
	global_load_dword v41, v5, s[18:19]
	s_add_u32 s18, s18, 0x24000
	s_addc_u32 s19, s19, 0
	global_load_dword v42, v4, s[18:19]
	global_load_dword v43, v5, s[18:19]
	s_add_u32 s18, s18, 0x24000
	s_addc_u32 s19, s19, 0
	global_load_dword v44, v4, s[18:19]
	global_load_dword v45, v5, s[18:19]
	s_add_u32 s18, s18, 0x24000
	s_addc_u32 s19, s19, 0
	global_load_dword v46, v4, s[18:19]
	global_load_dword v47, v5, s[18:19]
	s_add_u32 s18, s18, 0x24000
	s_addc_u32 s19, s19, 0
	global_load_dword v48, v4, s[18:19]
	global_load_dword v49, v5, s[18:19]
	s_add_u32 s18, s18, 0x24000
	s_addc_u32 s19, s19, 0
	global_load_dword v50, v4, s[18:19]
	global_load_dword v51, v5, s[18:19]
	s_add_u32 s18, s18, 0x24000
	s_addc_u32 s19, s19, 0
	global_load_dword v52, v4, s[18:19]
	global_load_dword v53, v5, s[18:19]
	s_add_u32 s18, s18, 0x24000
	s_addc_u32 s19, s19, 0
	global_load_dword v54, v4, s[18:19]
	global_load_dword v55, v5, s[18:19]
	s_add_u32 s18, s18, 0x24000
	s_addc_u32 s19, s19, 0
	global_load_dword v56, v4, s[18:19]
	global_load_dword v57, v5, s[18:19]
	s_add_u32 s18, s18, 0x24000
	s_addc_u32 s19, s19, 0
	global_load_dword v58, v4, s[18:19]
	global_load_dword v59, v5, s[18:19]
	s_add_u32 s18, s18, 0x24000
	s_addc_u32 s19, s19, 0
	s_waitcnt lgkmcnt(0)
	v_lshl_add_u64 v[0:1], v[0:1], 2, s[12:13]
	global_load_dword v0, v[0:1], off
	s_waitcnt vmcnt(1)
	v_pk_add_f32 v[2:3], v[2:3], v[20:21]
	v_pk_add_f32 v[2:3], v[2:3], v[22:23]
	v_pk_add_f32 v[2:3], v[2:3], v[32:33]
	v_pk_add_f32 v[2:3], v[2:3], v[34:35]
	v_pk_add_f32 v[2:3], v[2:3], v[36:37]
	v_pk_add_f32 v[2:3], v[2:3], v[38:39]
	v_pk_add_f32 v[2:3], v[2:3], v[40:41]
	v_pk_add_f32 v[2:3], v[2:3], v[42:43]
	v_pk_add_f32 v[2:3], v[2:3], v[44:45]
	v_pk_add_f32 v[2:3], v[2:3], v[46:47]
	v_pk_add_f32 v[2:3], v[2:3], v[48:49]
	v_pk_add_f32 v[2:3], v[2:3], v[50:51]
	v_pk_add_f32 v[2:3], v[2:3], v[52:53]
	v_pk_add_f32 v[2:3], v[2:3], v[54:55]
	v_pk_add_f32 v[2:3], v[2:3], v[56:57]
	v_pk_add_f32 v[2:3], v[2:3], v[58:59]
	v_add_f32_e32 v1, 1.0, v3
	v_add_u32_e32 v4, 0x200, v7
	v_cmp_lt_i32_e32 vcc, s24, v7
	v_lshl_add_u32 v3, v7, 2, 0
	s_or_b64 s[16:17], vcc, s[16:17]
	v_mov_b32_e32 v7, v4
	s_waitcnt vmcnt(0)
	v_mul_f32_e32 v0, v1, v0
	ds_write2st64_b32 v3, v0, v2 offset1:96
	s_andn2_b64 exec, exec, s[16:17]
	s_cbranch_execnz .LBB0_276

; #define LAS __attribute__((address_space(3)))
;     ...
;     for (int i = F.tid; i < 256 * 16; i += NTHREADS) *(LAS u32x4*)(skl + (i >> 4) * 272 + (i & 15) * 16) = *(const u32x4*)(SK + (size_t)(i >> 4) * 128 + (i & 15) * 8);
.LBB0_1921:
	s_or_b64 exec, exec, s[6:7]
	s_waitcnt lgkmcnt(0)
	s_barrier
	v_mbcnt_lo_u32_b32 v3, -1, 0
	v_mbcnt_hi_u32_b32 v3, -1, v3
	s_nop 0
	v_add_u32_e32 v4, s3, v3
	s_movk_i32 s3, 0x1000
	v_cmp_gt_i32_e32 vcc, s3, v4
	s_barrier
	s_and_saveexec_b64 s[6:7], vcc
	s_cbranch_execz .LBB0_1924
	v_and_b32_e32 v0, 15, v3
	v_lshrrev_b32_e32 v1, 4, v4
	v_lshlrev_b32_e32 v0, 4, v0
	s_movk_i32 s3, 0x110
	v_lshl_add_u32 v2, v1, 8, v0
	v_mad_u32_u24 v5, v1, s3, v0
	s_add_u32 s8, s56, 0x3e00000
	s_addc_u32 s9, s57, 0
	global_load_dwordx4 v[6:9], v2, s[8:9]
	s_add_u32 s8, s8, 0x2000
	s_addc_u32 s9, s9, 0
	global_load_dwordx4 v[10:13], v2, s[8:9]
	s_add_u32 s8, s8, 0x2000
	s_addc_u32 s9, s9, 0
	global_load_dwordx4 v[14:17], v2, s[8:9]
	s_add_u32 s8, s8, 0x2000
	s_addc_u32 s9, s9, 0
	global_load_dwordx4 v[18:21], v2, s[8:9]
	s_add_u32 s8, s8, 0x2000
	s_addc_u32 s9, s9, 0
	global_load_dwordx4 v[22:25], v2, s[8:9]
	s_add_u32 s8, s8, 0x2000
	s_addc_u32 s9, s9, 0
	global_load_dwordx4 v[26:29], v2, s[8:9]
	s_add_u32 s8, s8, 0x2000
	s_addc_u32 s9, s9, 0
	global_load_dwordx4 v[30:33], v2, s[8:9]
	s_add_u32 s8, s8, 0x2000
	s_addc_u32 s9, s9, 0
	global_load_dwordx4 v[34:37], v2, s[8:9]
	s_add_u32 s8, s8, 0x2000
	s_addc_u32 s9, s9, 0
	v_add_u32_e32 v38, 0x8800, v5
	s_waitcnt vmcnt(0)
	ds_write_b128 v5, v[6:9] offset:33792
	ds_write_b128 v5, v[10:13] offset:42496
	ds_write_b128 v5, v[14:17] offset:51200
	ds_write_b128 v5, v[18:21] offset:59904
	ds_write_b128 v38, v[22:25] offset:33792
	ds_write_b128 v38, v[26:29] offset:42496
	ds_write_b128 v38, v[30:33] offset:51200
	ds_write_b128 v38, v[34:37] offset:59904
